# P8 writes h3 into a padded-stride (8320B) buffer in the dead MIX/HALO region, P9 reads it: avoids L2-channel camping of epilogue stores; hand-written P8 epilogue
# speedup vs baseline: 1.0040x; 1.0040x over previous
;     const int tid = threadIdx.x, wid = __builtin_amdgcn_readfirstlane(tid >> 6), lane = tid & 63, wr = wid >> 2, wc = wid & 3, fr = lane & 15, fq = lane >> 4;
;     const int K = g.K, nt = K / BK;
;     unsigned voffA[2], voffB[2];
; #pragma unroll
;     for (int i = 0; i < 2; ++i) { int R, C; stage_rc(tid * 16 + i * 8192, R, C); const int Rb = Epi::PERM ? ((R & ~31) + perm32(R & 31)) : R;
;         voffA[i] = (unsigned)(R * g.lda + C) * 2u; voffB[i] = (unsigned)(Rb * g.ldb + C) * 2u; }
;     const size_t kstep = (size_t)(BK * 2);
;     const size_t hstepA = (size_t)HALF * g.lda * 2, hstepB = (size_t)HALF * g.ldb * 2;
;     const unsigned ldsw = (unsigned)wid * 1024u;
;     const unsigned ldsbase = (unsigned)__builtin_amdgcn_readfirstlane((int)((unsigned)(size_t)lds + ldsw)); (void)ldsw;
;     const int aoff = lds_byte(wr * 64 + fr, fq * 8), boff = lds_byte(wc * 32 + fr, fq * 8);
;     ...
;     Unit cur, nxt; int ui = 0;
;     if (!S.next(0, cur)) return;
; __global__ void __launch_bounds__(NWAVES * 64, 2) fwd_kernel(Args args) {
;     ...
;     if (IN(8)) {
;         pg8::Gemm g{FB, WDN, FF, FF, FF, 1, 1 << 30, 0, 0, 0, 0, 0}; pg8::StaticOrder S; S.init(MTOK / 256, DM / 256, G, bx, 4);
;         { pg8::EpiResid<true> E{HB, HB, rsq3, nullptr, DM, nullptr}; pg8::gemm_phase(ring, scr, g, S, E); }
.LBB0_1339:
	v_readlane_b32 s0, v244, 2
	v_readlane_b32 s14, v244, 16
	v_readlane_b32 s15, v244, 17
	s_add_u32 s34, s14, 0x60000
	s_addc_u32 s35, s15, 0
	v_readlane_b32 s1, v244, 3
	s_cmp_lt_i32 s96, 9
	v_readlane_b32 s2, v244, 4
	v_readlane_b32 s3, v244, 5
	s_cselect_b64 s[0:1], -1, 0
	s_cmp_gt_i32 s97, 8
	s_cselect_b64 s[2:3], -1, 0
	s_and_b64 s[0:1], s[0:1], s[2:3]
	s_andn2_b64 vcc, exec, s[0:1]
	v_readlane_b32 s4, v244, 6
	v_readlane_b32 s5, v244, 7
	v_readlane_b32 s6, v244, 8
	v_readlane_b32 s7, v244, 9
	v_readlane_b32 s8, v244, 10
	v_readlane_b32 s9, v244, 11
	v_readlane_b32 s10, v244, 12
	v_readlane_b32 s11, v244, 13
	v_readlane_b32 s12, v244, 14
	v_readlane_b32 s13, v244, 15
	s_cbranch_vccnz .LBB0_1422
	s_add_u32 s98, s14, 0x3a600000
	s_addc_u32 s99, s15, 0
	v_readfirstlane_b32 s2, v0
	s_lshr_b32 s3, s2, 6
	s_cmpk_gt_i32 s16, 0x3ff
	s_cbranch_scc1 .LBB0_1368
	s_ashr_i32 s14, s16, 31
	s_lshr_b32 s0, s14, 29
	s_add_i32 s6, s16, s0
	s_and_b32 s0, s6, -8
	s_sub_i32 s4, s16, s0
	s_cmp_gt_i32 s4, -1
	s_cbranch_scc0 .LBB0_1343
	s_lshl_b32 s5, s4, 7
	s_ashr_i32 s0, s6, 3
	s_cbranch_execz .LBB0_1344
	s_branch .LBB0_1345

; __device__ __forceinline__ unsigned cvt_pk_bf16(float lo, float hi) { unsigned r; asm volatile("v_cvt_pk_bf16_f32 %0, %1, %2" : "=v"(r) : "v"(lo), "v"(hi)); return r; }
;     __device__ __forceinline__ void operator()(EPI_ARGS) const {
;         const int row0 = u.pm * BM + wr * 64 + fr, col0 = u.pn * BM + wc * 32 + 8 * fq;
;         float ssv[8], mxv[8];
; #pragma unroll
;         for (int ai = 0; ai < 2; ++ai) {
;             f32x4 r0[4][2], r1[4][2];
; #pragma unroll
;             for (int m = 0; m < 4; ++m)
; #pragma unroll
;                 for (int bj = 0; bj < 2; ++bj) { const size_t off = (size_t)(row0 + ai * HALF + m * 16) * ldc + col0 + bj * HALF;
;                     if (RES_BF16) { const u32x4 rw = *(const u32x4*)((const bf16*)resid + off); r0[m][bj] = __builtin_bit_cast(f32x4, rw); }
;                     else { r0[m][bj] = *(const f32x4*)((const float*)resid + off); r1[m][bj] = *(const f32x4*)((const float*)resid + off + 4); } }
; #pragma unroll
;             for (int m = 0; m < 4; ++m) { const int row = row0 + ai * HALF + m * 16; const size_t off = (size_t)row * ldc + col0; float ss = 0.f, mx = 0.f;
; #pragma unroll
;                 for (int bj = 0; bj < 2; ++bj) {
;                     f32x4 a0, a1;
;                     if (RES_BF16) { const u32x4 rw = __builtin_bit_cast(u32x4, r0[m][bj]); a0 = (f32x4){bf_lo(rw.x), bf_hi(rw.x), bf_lo(rw.y), bf_hi(rw.y)}; a1 = (f32x4){bf_lo(rw.z), bf_hi(rw.z), bf_lo(rw.w), bf_hi(rw.w)};
;                         if (RES_SCALE) { const float rf = rfac[row]; a0 = a0 * rf; a1 = a1 * rf; } }
;                     else { a0 = r0[m][bj]; a1 = r1[m][bj]; }
;                     const f32x4 v0 = acc[ai][bj][m][0] + a0, v1 = acc[ai][bj][m][1] + a1;
;                     u32x4 w; w.x = cvt_pk_bf16(v0[0], v0[1]); w.y = cvt_pk_bf16(v0[2], v0[3]); w.z = cvt_pk_bf16(v1[0], v1[1]); w.w = cvt_pk_bf16(v1[2], v1[3]); *(u32x4*)(ob + off + bj * HALF) = w;
;                     ss += (v0[0] * v0[0] + v0[1] * v0[1]) + (v0[2] * v0[2] + v0[3] * v0[3]) + (v1[0] * v1[0] + v1[1] * v1[1]) + (v1[2] * v1[2] + v1[3] * v1[3]);
;                     if (rowmax) mx = fmaxf(mx, fmaxf(fmaxf(fmaxf(fabsf(v0[0]), fabsf(v0[1])), fmaxf(fabsf(v0[2]), fabsf(v0[3]))), fmaxf(fmaxf(fabsf(v1[0]), fabsf(v1[1])), fmaxf(fabsf(v1[2]), fabsf(v1[3]))))); }
;                 ss += __shfl_xor(ss, 16); ss += __shfl_xor(ss, 32); ssv[ai * 4 + m] = ss;
.LBB0_1364:
.Lmy_p8_epi_begin:
	s_nop 7
	v_and_b32_e32 v255, 63, v0
	v_xor_b32_e32 v252, 16, v255
	v_xor_b32_e32 v253, 32, v255
	v_lshlrev_b32_e32 v252, 2, v252
	v_lshlrev_b32_e32 v253, 2, v253
	v_lshl_add_u32 v245, s72, 8, v157
	v_lshl_or_b32 v246, s73, 8, v159
	v_lshlrev_b32_e32 v245, 13, v245
	v_lshl_add_u32 v245, v246, 1, v245
	global_load_dwordx4 v[130:133], v245, s[52:53]
	global_load_dwordx4 v[134:137], v245, s[52:53] offset:256
	v_add_u32_e32 v246, 0x20000, v245
	global_load_dwordx4 v[142:145], v246, s[52:53]
	global_load_dwordx4 v[146:149], v246, s[52:53] offset:256
	v_add_u32_e32 v255, 0x40000, v245
	global_load_dwordx4 v[150:153], v255, s[52:53]
	global_load_dwordx4 v[166:169], v255, s[52:53] offset:256
	v_add_u32_e32 v246, 0x60000, v245
	global_load_dwordx4 v[170:173], v246, s[52:53]
	global_load_dwordx4 v[174:177], v246, s[52:53] offset:256
	v_add_u32_e32 v255, 0x100000, v245
	global_load_dwordx4 v[178:181], v255, s[52:53]
	global_load_dwordx4 v[182:185], v255, s[52:53] offset:256
	v_add_u32_e32 v246, 0x120000, v245
	global_load_dwordx4 v[186:189], v246, s[52:53]
	global_load_dwordx4 v[190:193], v246, s[52:53] offset:256
	v_add_u32_e32 v255, 0x140000, v245
	global_load_dwordx4 v[194:197], v255, s[52:53]
	global_load_dwordx4 v[198:201], v255, s[52:53] offset:256
	v_add_u32_e32 v246, 0x160000, v245
	global_load_dwordx4 v[202:205], v246, s[52:53]
	global_load_dwordx4 v[206:209], v246, s[52:53] offset:256
	v_lshl_add_u32 v245, s72, 8, v157
	v_mul_u32_u24_e32 v245, 0x2080, v245
	v_lshl_or_b32 v246, s73, 8, v159
	v_lshl_add_u32 v245, v246, 1, v245
	s_waitcnt vmcnt(15)
	v_lshlrev_b32_e32 v248, 16, v130
	v_and_b32_e32 v249, 0xffff0000, v130
	v_lshlrev_b32_e32 v250, 16, v131
	v_and_b32_e32 v251, 0xffff0000, v131
	v_pk_add_f32 v[126:127], v[126:127], v[248:249]
	v_pk_add_f32 v[128:129], v[128:129], v[250:251]
	v_lshlrev_b32_e32 v248, 16, v132
	v_and_b32_e32 v249, 0xffff0000, v132
	v_lshlrev_b32_e32 v250, 16, v133
	v_and_b32_e32 v251, 0xffff0000, v133
	v_pk_add_f32 v[122:123], v[122:123], v[248:249]
	v_pk_add_f32 v[124:125], v[124:125], v[250:251]
	v_cvt_pk_bf16_f32 v130, v126, v127
	v_cvt_pk_bf16_f32 v131, v128, v129
	v_cvt_pk_bf16_f32 v132, v122, v123
	v_cvt_pk_bf16_f32 v133, v124, v125
	global_store_dwordx4 v245, v[130:133], s[98:99]
	v_mul_f32_e32 v247, v126, v126
	v_fmac_f32_e32 v247, v127, v127
	v_fmac_f32_e32 v247, v128, v128
	v_fmac_f32_e32 v247, v129, v129
	v_mul_f32_e32 v254, v122, v122
	v_fmac_f32_e32 v254, v123, v123
	v_fmac_f32_e32 v254, v124, v124
	v_fmac_f32_e32 v254, v125, v125
	s_waitcnt vmcnt(15)
	v_lshlrev_b32_e32 v248, 16, v134
	v_and_b32_e32 v249, 0xffff0000, v134
	v_lshlrev_b32_e32 v250, 16, v135
	v_and_b32_e32 v251, 0xffff0000, v135
	v_pk_add_f32 v[118:119], v[118:119], v[248:249]
	v_pk_add_f32 v[120:121], v[120:121], v[250:251]
	v_lshlrev_b32_e32 v248, 16, v136
	v_and_b32_e32 v249, 0xffff0000, v136
	v_lshlrev_b32_e32 v250, 16, v137
	v_and_b32_e32 v251, 0xffff0000, v137
	v_pk_add_f32 v[114:115], v[114:115], v[248:249]
	v_pk_add_f32 v[116:117], v[116:117], v[250:251]
	v_cvt_pk_bf16_f32 v134, v118, v119
	v_cvt_pk_bf16_f32 v135, v120, v121
	v_cvt_pk_bf16_f32 v136, v114, v115
	v_cvt_pk_bf16_f32 v137, v116, v117
	global_store_dwordx4 v245, v[134:137], s[98:99] offset:256
	v_fmac_f32_e32 v247, v118, v118
	v_fmac_f32_e32 v247, v119, v119
	v_fmac_f32_e32 v247, v120, v120
	v_fmac_f32_e32 v247, v121, v121
	v_fmac_f32_e32 v254, v114, v114
	v_fmac_f32_e32 v254, v115, v115
	v_fmac_f32_e32 v254, v116, v116
	v_fmac_f32_e32 v254, v117, v117
	v_add_f32_e32 v126, v247, v254
	s_waitcnt vmcnt(15)
	v_lshlrev_b32_e32 v248, 16, v142
	v_and_b32_e32 v249, 0xffff0000, v142
	v_lshlrev_b32_e32 v250, 16, v143
	v_and_b32_e32 v251, 0xffff0000, v143
	v_pk_add_f32 v[110:111], v[110:111], v[248:249]
	v_pk_add_f32 v[112:113], v[112:113], v[250:251]
	v_lshlrev_b32_e32 v248, 16, v144
	v_and_b32_e32 v249, 0xffff0000, v144
	v_lshlrev_b32_e32 v250, 16, v145
	v_and_b32_e32 v251, 0xffff0000, v145
	v_pk_add_f32 v[106:107], v[106:107], v[248:249]
	v_pk_add_f32 v[108:109], v[108:109], v[250:251]
	v_cvt_pk_bf16_f32 v142, v110, v111
	v_cvt_pk_bf16_f32 v143, v112, v113
	v_cvt_pk_bf16_f32 v144, v106, v107
	v_cvt_pk_bf16_f32 v145, v108, v109
	v_add_u32_e32 v246, 0x20800, v245
	global_store_dwordx4 v246, v[142:145], s[98:99]
	v_mul_f32_e32 v247, v110, v110
	v_fmac_f32_e32 v247, v111, v111
	v_fmac_f32_e32 v247, v112, v112
	v_fmac_f32_e32 v247, v113, v113
	v_mul_f32_e32 v254, v106, v106
	v_fmac_f32_e32 v254, v107, v107
	v_fmac_f32_e32 v254, v108, v108
	v_fmac_f32_e32 v254, v109, v109
	s_waitcnt vmcnt(15)
	v_lshlrev_b32_e32 v248, 16, v146
	v_and_b32_e32 v249, 0xffff0000, v146
	v_lshlrev_b32_e32 v250, 16, v147
	v_and_b32_e32 v251, 0xffff0000, v147
	v_pk_add_f32 v[102:103], v[102:103], v[248:249]
	v_pk_add_f32 v[104:105], v[104:105], v[250:251]
	v_lshlrev_b32_e32 v248, 16, v148
	v_and_b32_e32 v249, 0xffff0000, v148
	v_lshlrev_b32_e32 v250, 16, v149
	v_and_b32_e32 v251, 0xffff0000, v149
	v_pk_add_f32 v[98:99], v[98:99], v[248:249]
	v_pk_add_f32 v[100:101], v[100:101], v[250:251]
	v_cvt_pk_bf16_f32 v146, v102, v103
	v_cvt_pk_bf16_f32 v147, v104, v105
	v_cvt_pk_bf16_f32 v148, v98, v99
	v_cvt_pk_bf16_f32 v149, v100, v101
	v_add_u32_e32 v255, 0x20800, v245
	global_store_dwordx4 v255, v[146:149], s[98:99] offset:256
	v_fmac_f32_e32 v247, v102, v102
	v_fmac_f32_e32 v247, v103, v103
	v_fmac_f32_e32 v247, v104, v104
	v_fmac_f32_e32 v247, v105, v105
	v_fmac_f32_e32 v254, v98, v98
	v_fmac_f32_e32 v254, v99, v99
	v_fmac_f32_e32 v254, v100, v100
	v_fmac_f32_e32 v254, v101, v101
	v_add_f32_e32 v110, v247, v254
	s_waitcnt vmcnt(15)
; __device__ __forceinline__ unsigned cvt_pk_bf16(float lo, float hi) { unsigned r; asm volatile("v_cvt_pk_bf16_f32 %0, %1, %2" : "=v"(r) : "v"(lo), "v"(hi)); return r; }
; __device__ __forceinline__ float bf_lo(unsigned w) { return __uint_as_float(w << 16); }
; __device__ __forceinline__ float bf_hi(unsigned w) { return __uint_as_float(w & 0xffff0000u); }
;     __device__ __forceinline__ void operator()(EPI_ARGS) const {
;     ...
;             for (int m = 0; m < 4; ++m) { const int row = row0 + ai * HALF + m * 16; const size_t off = (size_t)row * ldc + col0; float ss = 0.f, mx = 0.f;
; #pragma unroll
;                 for (int bj = 0; bj < 2; ++bj) {
;                     f32x4 a0, a1;
;                     if (RES_BF16) { const u32x4 rw = __builtin_bit_cast(u32x4, r0[m][bj]); a0 = (f32x4){bf_lo(rw.x), bf_hi(rw.x), bf_lo(rw.y), bf_hi(rw.y)}; a1 = (f32x4){bf_lo(rw.z), bf_hi(rw.z), bf_lo(rw.w), bf_hi(rw.w)};
;                         if (RES_SCALE) { const float rf = rfac[row]; a0 = a0 * rf; a1 = a1 * rf; } }
;                     else { a0 = r0[m][bj]; a1 = r1[m][bj]; }
;                     const f32x4 v0 = acc[ai][bj][m][0] + a0, v1 = acc[ai][bj][m][1] + a1;
;                     u32x4 w; w.x = cvt_pk_bf16(v0[0], v0[1]); w.y = cvt_pk_bf16(v0[2], v0[3]); w.z = cvt_pk_bf16(v1[0], v1[1]); w.w = cvt_pk_bf16(v1[2], v1[3]); *(u32x4*)(ob + off + bj * HALF) = w;
;                     ss += (v0[0] * v0[0] + v0[1] * v0[1]) + (v0[2] * v0[2] + v0[3] * v0[3]) + (v1[0] * v1[0] + v1[1] * v1[1]) + (v1[2] * v1[2] + v1[3] * v1[3]);
	v_lshlrev_b32_e32 v248, 16, v150
	v_and_b32_e32 v249, 0xffff0000, v150
	v_lshlrev_b32_e32 v250, 16, v151
	v_and_b32_e32 v251, 0xffff0000, v151
	v_pk_add_f32 v[94:95], v[94:95], v[248:249]
	v_pk_add_f32 v[96:97], v[96:97], v[250:251]
	v_lshlrev_b32_e32 v248, 16, v152
	v_and_b32_e32 v249, 0xffff0000, v152
	v_lshlrev_b32_e32 v250, 16, v153
	v_and_b32_e32 v251, 0xffff0000, v153
	v_pk_add_f32 v[90:91], v[90:91], v[248:249]
	v_pk_add_f32 v[92:93], v[92:93], v[250:251]
	v_cvt_pk_bf16_f32 v150, v94, v95
	v_cvt_pk_bf16_f32 v151, v96, v97
	v_cvt_pk_bf16_f32 v152, v90, v91
	v_cvt_pk_bf16_f32 v153, v92, v93
	v_add_u32_e32 v246, 0x41000, v245
	global_store_dwordx4 v246, v[150:153], s[98:99]
	v_mul_f32_e32 v247, v94, v94
	v_fmac_f32_e32 v247, v95, v95
	v_fmac_f32_e32 v247, v96, v96
	v_fmac_f32_e32 v247, v97, v97
	v_mul_f32_e32 v254, v90, v90
	v_fmac_f32_e32 v254, v91, v91
	v_fmac_f32_e32 v254, v92, v92
	v_fmac_f32_e32 v254, v93, v93
	s_waitcnt vmcnt(15)
	v_lshlrev_b32_e32 v248, 16, v166
	v_and_b32_e32 v249, 0xffff0000, v166
	v_lshlrev_b32_e32 v250, 16, v167
	v_and_b32_e32 v251, 0xffff0000, v167
	v_pk_add_f32 v[86:87], v[86:87], v[248:249]
	v_pk_add_f32 v[88:89], v[88:89], v[250:251]
	v_lshlrev_b32_e32 v248, 16, v168
	v_and_b32_e32 v249, 0xffff0000, v168
	v_lshlrev_b32_e32 v250, 16, v169
	v_and_b32_e32 v251, 0xffff0000, v169
	v_pk_add_f32 v[82:83], v[82:83], v[248:249]
	v_pk_add_f32 v[84:85], v[84:85], v[250:251]
	v_cvt_pk_bf16_f32 v166, v86, v87
	v_cvt_pk_bf16_f32 v167, v88, v89
	v_cvt_pk_bf16_f32 v168, v82, v83
	v_cvt_pk_bf16_f32 v169, v84, v85
	v_add_u32_e32 v255, 0x41000, v245
	global_store_dwordx4 v255, v[166:169], s[98:99] offset:256
	v_fmac_f32_e32 v247, v86, v86
	v_fmac_f32_e32 v247, v87, v87
	v_fmac_f32_e32 v247, v88, v88
	v_fmac_f32_e32 v247, v89, v89
	v_fmac_f32_e32 v254, v82, v82
	v_fmac_f32_e32 v254, v83, v83
	v_fmac_f32_e32 v254, v84, v84
	v_fmac_f32_e32 v254, v85, v85
	v_add_f32_e32 v94, v247, v254
	s_waitcnt vmcnt(15)
	v_lshlrev_b32_e32 v248, 16, v170
	v_and_b32_e32 v249, 0xffff0000, v170
	v_lshlrev_b32_e32 v250, 16, v171
	v_and_b32_e32 v251, 0xffff0000, v171
	v_pk_add_f32 v[78:79], v[78:79], v[248:249]
	v_pk_add_f32 v[80:81], v[80:81], v[250:251]
	v_lshlrev_b32_e32 v248, 16, v172
	v_and_b32_e32 v249, 0xffff0000, v172
	v_lshlrev_b32_e32 v250, 16, v173
	v_and_b32_e32 v251, 0xffff0000, v173
	v_pk_add_f32 v[74:75], v[74:75], v[248:249]
	v_pk_add_f32 v[76:77], v[76:77], v[250:251]
	v_cvt_pk_bf16_f32 v170, v78, v79
	v_cvt_pk_bf16_f32 v171, v80, v81
	v_cvt_pk_bf16_f32 v172, v74, v75
	v_cvt_pk_bf16_f32 v173, v76, v77
	v_add_u32_e32 v246, 0x61800, v245
	global_store_dwordx4 v246, v[170:173], s[98:99]
	v_mul_f32_e32 v247, v78, v78
	v_fmac_f32_e32 v247, v79, v79
	v_fmac_f32_e32 v247, v80, v80
	v_fmac_f32_e32 v247, v81, v81
	v_mul_f32_e32 v254, v74, v74
	v_fmac_f32_e32 v254, v75, v75
	v_fmac_f32_e32 v254, v76, v76
	v_fmac_f32_e32 v254, v77, v77
	s_waitcnt vmcnt(15)
	v_lshlrev_b32_e32 v248, 16, v174
	v_and_b32_e32 v249, 0xffff0000, v174
	v_lshlrev_b32_e32 v250, 16, v175
	v_and_b32_e32 v251, 0xffff0000, v175
	v_pk_add_f32 v[70:71], v[70:71], v[248:249]
	v_pk_add_f32 v[72:73], v[72:73], v[250:251]
	v_lshlrev_b32_e32 v248, 16, v176
	v_and_b32_e32 v249, 0xffff0000, v176
	v_lshlrev_b32_e32 v250, 16, v177
	v_and_b32_e32 v251, 0xffff0000, v177
	v_pk_add_f32 v[66:67], v[66:67], v[248:249]
	v_pk_add_f32 v[68:69], v[68:69], v[250:251]
	v_cvt_pk_bf16_f32 v174, v70, v71
	v_cvt_pk_bf16_f32 v175, v72, v73
	v_cvt_pk_bf16_f32 v176, v66, v67
	v_cvt_pk_bf16_f32 v177, v68, v69
	v_add_u32_e32 v255, 0x61800, v245
	global_store_dwordx4 v255, v[174:177], s[98:99] offset:256
	v_fmac_f32_e32 v247, v70, v70
	v_fmac_f32_e32 v247, v71, v71
	v_fmac_f32_e32 v247, v72, v72
	v_fmac_f32_e32 v247, v73, v73
	v_fmac_f32_e32 v254, v66, v66
	v_fmac_f32_e32 v254, v67, v67
	v_fmac_f32_e32 v254, v68, v68
	v_fmac_f32_e32 v254, v69, v69
	v_add_f32_e32 v78, v247, v254
	s_waitcnt vmcnt(15)
	v_lshlrev_b32_e32 v248, 16, v178
	v_and_b32_e32 v249, 0xffff0000, v178
	v_lshlrev_b32_e32 v250, 16, v179
	v_and_b32_e32 v251, 0xffff0000, v179
	v_pk_add_f32 v[62:63], v[62:63], v[248:249]
	v_pk_add_f32 v[64:65], v[64:65], v[250:251]
	v_lshlrev_b32_e32 v248, 16, v180
	v_and_b32_e32 v249, 0xffff0000, v180
	v_lshlrev_b32_e32 v250, 16, v181
	v_and_b32_e32 v251, 0xffff0000, v181
	v_pk_add_f32 v[58:59], v[58:59], v[248:249]
	v_pk_add_f32 v[60:61], v[60:61], v[250:251]
	v_cvt_pk_bf16_f32 v178, v62, v63
	v_cvt_pk_bf16_f32 v179, v64, v65
	v_cvt_pk_bf16_f32 v180, v58, v59
	v_cvt_pk_bf16_f32 v181, v60, v61
	v_add_u32_e32 v246, 0x104000, v245
	global_store_dwordx4 v246, v[178:181], s[98:99]
	v_mul_f32_e32 v247, v62, v62
	v_fmac_f32_e32 v247, v63, v63
	v_fmac_f32_e32 v247, v64, v64
	v_fmac_f32_e32 v247, v65, v65
	v_mul_f32_e32 v254, v58, v58
	v_fmac_f32_e32 v254, v59, v59
	v_fmac_f32_e32 v254, v60, v60
	v_fmac_f32_e32 v254, v61, v61
	s_waitcnt vmcnt(15)
	v_lshlrev_b32_e32 v248, 16, v182
	v_and_b32_e32 v249, 0xffff0000, v182
	v_lshlrev_b32_e32 v250, 16, v183
	v_and_b32_e32 v251, 0xffff0000, v183
	v_pk_add_f32 v[54:55], v[54:55], v[248:249]
	v_pk_add_f32 v[56:57], v[56:57], v[250:251]
	v_lshlrev_b32_e32 v248, 16, v184
	v_and_b32_e32 v249, 0xffff0000, v184
	v_lshlrev_b32_e32 v250, 16, v185
	v_and_b32_e32 v251, 0xffff0000, v185
	v_pk_add_f32 v[50:51], v[50:51], v[248:249]
	v_pk_add_f32 v[52:53], v[52:53], v[250:251]
	v_cvt_pk_bf16_f32 v182, v54, v55
	v_cvt_pk_bf16_f32 v183, v56, v57
	v_cvt_pk_bf16_f32 v184, v50, v51
	v_cvt_pk_bf16_f32 v185, v52, v53
	v_add_u32_e32 v255, 0x104000, v245
	global_store_dwordx4 v255, v[182:185], s[98:99] offset:256
	v_fmac_f32_e32 v247, v54, v54
	v_fmac_f32_e32 v247, v55, v55
	v_fmac_f32_e32 v247, v56, v56
	v_fmac_f32_e32 v247, v57, v57
	v_fmac_f32_e32 v254, v50, v50
	v_fmac_f32_e32 v254, v51, v51
	v_fmac_f32_e32 v254, v52, v52
	v_fmac_f32_e32 v254, v53, v53
	v_add_f32_e32 v62, v247, v254
	s_waitcnt vmcnt(15)
; __device__ __forceinline__ unsigned cvt_pk_bf16(float lo, float hi) { unsigned r; asm volatile("v_cvt_pk_bf16_f32 %0, %1, %2" : "=v"(r) : "v"(lo), "v"(hi)); return r; }
; __device__ __forceinline__ float bf_lo(unsigned w) { return __uint_as_float(w << 16); }
; __device__ __forceinline__ float bf_hi(unsigned w) { return __uint_as_float(w & 0xffff0000u); }
;     __device__ __forceinline__ void operator()(EPI_ARGS) const {
;     ...
;             for (int m = 0; m < 4; ++m) { const int row = row0 + ai * HALF + m * 16; const size_t off = (size_t)row * ldc + col0; float ss = 0.f, mx = 0.f;
; #pragma unroll
;                 for (int bj = 0; bj < 2; ++bj) {
;                     f32x4 a0, a1;
;                     if (RES_BF16) { const u32x4 rw = __builtin_bit_cast(u32x4, r0[m][bj]); a0 = (f32x4){bf_lo(rw.x), bf_hi(rw.x), bf_lo(rw.y), bf_hi(rw.y)}; a1 = (f32x4){bf_lo(rw.z), bf_hi(rw.z), bf_lo(rw.w), bf_hi(rw.w)};
;                         if (RES_SCALE) { const float rf = rfac[row]; a0 = a0 * rf; a1 = a1 * rf; } }
;                     else { a0 = r0[m][bj]; a1 = r1[m][bj]; }
;                     const f32x4 v0 = acc[ai][bj][m][0] + a0, v1 = acc[ai][bj][m][1] + a1;
;                     u32x4 w; w.x = cvt_pk_bf16(v0[0], v0[1]); w.y = cvt_pk_bf16(v0[2], v0[3]); w.z = cvt_pk_bf16(v1[0], v1[1]); w.w = cvt_pk_bf16(v1[2], v1[3]); *(u32x4*)(ob + off + bj * HALF) = w;
;                     ss += (v0[0] * v0[0] + v0[1] * v0[1]) + (v0[2] * v0[2] + v0[3] * v0[3]) + (v1[0] * v1[0] + v1[1] * v1[1]) + (v1[2] * v1[2] + v1[3] * v1[3]);
	v_lshlrev_b32_e32 v248, 16, v186
	v_and_b32_e32 v249, 0xffff0000, v186
	v_lshlrev_b32_e32 v250, 16, v187
	v_and_b32_e32 v251, 0xffff0000, v187
	v_pk_add_f32 v[46:47], v[46:47], v[248:249]
	v_pk_add_f32 v[48:49], v[48:49], v[250:251]
	v_lshlrev_b32_e32 v248, 16, v188
	v_and_b32_e32 v249, 0xffff0000, v188
	v_lshlrev_b32_e32 v250, 16, v189
	v_and_b32_e32 v251, 0xffff0000, v189
	v_pk_add_f32 v[42:43], v[42:43], v[248:249]
	v_pk_add_f32 v[44:45], v[44:45], v[250:251]
	v_cvt_pk_bf16_f32 v186, v46, v47
	v_cvt_pk_bf16_f32 v187, v48, v49
	v_cvt_pk_bf16_f32 v188, v42, v43
	v_cvt_pk_bf16_f32 v189, v44, v45
	v_add_u32_e32 v246, 0x124800, v245
	global_store_dwordx4 v246, v[186:189], s[98:99]
	v_mul_f32_e32 v247, v46, v46
	v_fmac_f32_e32 v247, v47, v47
	v_fmac_f32_e32 v247, v48, v48
	v_fmac_f32_e32 v247, v49, v49
	v_mul_f32_e32 v254, v42, v42
	v_fmac_f32_e32 v254, v43, v43
	v_fmac_f32_e32 v254, v44, v44
	v_fmac_f32_e32 v254, v45, v45
	s_waitcnt vmcnt(15)
	v_lshlrev_b32_e32 v248, 16, v190
	v_and_b32_e32 v249, 0xffff0000, v190
	v_lshlrev_b32_e32 v250, 16, v191
	v_and_b32_e32 v251, 0xffff0000, v191
	v_pk_add_f32 v[38:39], v[38:39], v[248:249]
	v_pk_add_f32 v[40:41], v[40:41], v[250:251]
	v_lshlrev_b32_e32 v248, 16, v192
	v_and_b32_e32 v249, 0xffff0000, v192
	v_lshlrev_b32_e32 v250, 16, v193
	v_and_b32_e32 v251, 0xffff0000, v193
	v_pk_add_f32 v[34:35], v[34:35], v[248:249]
	v_pk_add_f32 v[36:37], v[36:37], v[250:251]
	v_cvt_pk_bf16_f32 v190, v38, v39
	v_cvt_pk_bf16_f32 v191, v40, v41
	v_cvt_pk_bf16_f32 v192, v34, v35
	v_cvt_pk_bf16_f32 v193, v36, v37
	v_add_u32_e32 v255, 0x124800, v245
	global_store_dwordx4 v255, v[190:193], s[98:99] offset:256
	v_fmac_f32_e32 v247, v38, v38
	v_fmac_f32_e32 v247, v39, v39
	v_fmac_f32_e32 v247, v40, v40
	v_fmac_f32_e32 v247, v41, v41
	v_fmac_f32_e32 v254, v34, v34
	v_fmac_f32_e32 v254, v35, v35
	v_fmac_f32_e32 v254, v36, v36
	v_fmac_f32_e32 v254, v37, v37
	v_add_f32_e32 v46, v247, v254
	s_waitcnt vmcnt(15)
	v_lshlrev_b32_e32 v248, 16, v194
	v_and_b32_e32 v249, 0xffff0000, v194
	v_lshlrev_b32_e32 v250, 16, v195
	v_and_b32_e32 v251, 0xffff0000, v195
	v_pk_add_f32 v[30:31], v[30:31], v[248:249]
	v_pk_add_f32 v[32:33], v[32:33], v[250:251]
	v_lshlrev_b32_e32 v248, 16, v196
	v_and_b32_e32 v249, 0xffff0000, v196
	v_lshlrev_b32_e32 v250, 16, v197
	v_and_b32_e32 v251, 0xffff0000, v197
	v_pk_add_f32 v[26:27], v[26:27], v[248:249]
	v_pk_add_f32 v[28:29], v[28:29], v[250:251]
	v_cvt_pk_bf16_f32 v194, v30, v31
	v_cvt_pk_bf16_f32 v195, v32, v33
	v_cvt_pk_bf16_f32 v196, v26, v27
	v_cvt_pk_bf16_f32 v197, v28, v29
	v_add_u32_e32 v246, 0x145000, v245
	global_store_dwordx4 v246, v[194:197], s[98:99]
	v_mul_f32_e32 v247, v30, v30
	v_fmac_f32_e32 v247, v31, v31
	v_fmac_f32_e32 v247, v32, v32
	v_fmac_f32_e32 v247, v33, v33
	v_mul_f32_e32 v254, v26, v26
	v_fmac_f32_e32 v254, v27, v27
	v_fmac_f32_e32 v254, v28, v28
	v_fmac_f32_e32 v254, v29, v29
	s_waitcnt vmcnt(15)
	v_lshlrev_b32_e32 v248, 16, v198
	v_and_b32_e32 v249, 0xffff0000, v198
	v_lshlrev_b32_e32 v250, 16, v199
	v_and_b32_e32 v251, 0xffff0000, v199
	v_pk_add_f32 v[22:23], v[22:23], v[248:249]
	v_pk_add_f32 v[24:25], v[24:25], v[250:251]
	v_lshlrev_b32_e32 v248, 16, v200
	v_and_b32_e32 v249, 0xffff0000, v200
	v_lshlrev_b32_e32 v250, 16, v201
	v_and_b32_e32 v251, 0xffff0000, v201
	v_pk_add_f32 v[18:19], v[18:19], v[248:249]
	v_pk_add_f32 v[20:21], v[20:21], v[250:251]
	v_cvt_pk_bf16_f32 v198, v22, v23
	v_cvt_pk_bf16_f32 v199, v24, v25
	v_cvt_pk_bf16_f32 v200, v18, v19
	v_cvt_pk_bf16_f32 v201, v20, v21
	v_add_u32_e32 v255, 0x145000, v245
	global_store_dwordx4 v255, v[198:201], s[98:99] offset:256
	v_fmac_f32_e32 v247, v22, v22
	v_fmac_f32_e32 v247, v23, v23
	v_fmac_f32_e32 v247, v24, v24
	v_fmac_f32_e32 v247, v25, v25
	v_fmac_f32_e32 v254, v18, v18
	v_fmac_f32_e32 v254, v19, v19
	v_fmac_f32_e32 v254, v20, v20
	v_fmac_f32_e32 v254, v21, v21
	v_add_f32_e32 v30, v247, v254
	s_waitcnt vmcnt(15)
; __device__ __forceinline__ unsigned cvt_pk_bf16(float lo, float hi) { unsigned r; asm volatile("v_cvt_pk_bf16_f32 %0, %1, %2" : "=v"(r) : "v"(lo), "v"(hi)); return r; }
;     __device__ __forceinline__ void operator()(EPI_ARGS) const {
;     ...
;                     const f32x4 v0 = acc[ai][bj][m][0] + a0, v1 = acc[ai][bj][m][1] + a1;
;                     u32x4 w; w.x = cvt_pk_bf16(v0[0], v0[1]); w.y = cvt_pk_bf16(v0[2], v0[3]); w.z = cvt_pk_bf16(v1[0], v1[1]); w.w = cvt_pk_bf16(v1[2], v1[3]); *(u32x4*)(ob + off + bj * HALF) = w;
;                     ss += (v0[0] * v0[0] + v0[1] * v0[1]) + (v0[2] * v0[2] + v0[3] * v0[3]) + (v1[0] * v1[0] + v1[1] * v1[1]) + (v1[2] * v1[2] + v1[3] * v1[3]);
;                     if (rowmax) mx = fmaxf(mx, fmaxf(fmaxf(fmaxf(fabsf(v0[0]), fabsf(v0[1])), fmaxf(fabsf(v0[2]), fabsf(v0[3]))), fmaxf(fmaxf(fabsf(v1[0]), fabsf(v1[1])), fmaxf(fabsf(v1[2]), fabsf(v1[3]))))); }
;                 ss += __shfl_xor(ss, 16); ss += __shfl_xor(ss, 32); ssv[ai * 4 + m] = ss;
;                 if (rowmax) { mx = fmaxf(mx, __shfl_xor(mx, 16)); mx = fmaxf(mx, __shfl_xor(mx, 32)); } mxv[ai * 4 + m] = mx; }
;             asm volatile("" ::: "memory"); }
;         float s0 = 0.f, s1 = 0.f, m0 = 0.f, m1 = 0.f;
; #pragma unroll
;         for (int k = 0; k < 8; ++k) if ((k >> 1) == fq) { if (k & 1) { s1 = ssv[k]; m1 = mxv[k]; } else { s0 = ssv[k]; m0 = mxv[k]; } }
;         const int rq = row0 + (fq >> 1) * HALF + (fq & 1) * 32;
;         __hip_atomic_fetch_add(rowsq + rq, s0, __ATOMIC_RELAXED, __HIP_MEMORY_SCOPE_AGENT); __hip_atomic_fetch_add(rowsq + rq + 16, s1, __ATOMIC_RELAXED, __HIP_MEMORY_SCOPE_AGENT);
	v_lshlrev_b32_e32 v248, 16, v202
	v_and_b32_e32 v249, 0xffff0000, v202
	v_lshlrev_b32_e32 v250, 16, v203
	v_and_b32_e32 v251, 0xffff0000, v203
	v_pk_add_f32 v[14:15], v[14:15], v[248:249]
	v_pk_add_f32 v[16:17], v[16:17], v[250:251]
	v_lshlrev_b32_e32 v248, 16, v204
	v_and_b32_e32 v249, 0xffff0000, v204
	v_lshlrev_b32_e32 v250, 16, v205
	v_and_b32_e32 v251, 0xffff0000, v205
	v_pk_add_f32 v[10:11], v[10:11], v[248:249]
	v_pk_add_f32 v[12:13], v[12:13], v[250:251]
	v_cvt_pk_bf16_f32 v202, v14, v15
	v_cvt_pk_bf16_f32 v203, v16, v17
	v_cvt_pk_bf16_f32 v204, v10, v11
	v_cvt_pk_bf16_f32 v205, v12, v13
	v_add_u32_e32 v246, 0x165800, v245
	global_store_dwordx4 v246, v[202:205], s[98:99]
	v_mul_f32_e32 v247, v14, v14
	v_fmac_f32_e32 v247, v15, v15
	v_fmac_f32_e32 v247, v16, v16
	v_fmac_f32_e32 v247, v17, v17
	v_mul_f32_e32 v254, v10, v10
	v_fmac_f32_e32 v254, v11, v11
	v_fmac_f32_e32 v254, v12, v12
	v_fmac_f32_e32 v254, v13, v13
	s_waitcnt vmcnt(15)
	v_lshlrev_b32_e32 v248, 16, v206
	v_and_b32_e32 v249, 0xffff0000, v206
	v_lshlrev_b32_e32 v250, 16, v207
	v_and_b32_e32 v251, 0xffff0000, v207
	v_pk_add_f32 v[6:7], v[6:7], v[248:249]
	v_pk_add_f32 v[8:9], v[8:9], v[250:251]
	v_lshlrev_b32_e32 v248, 16, v208
	v_and_b32_e32 v249, 0xffff0000, v208
	v_lshlrev_b32_e32 v250, 16, v209
	v_and_b32_e32 v251, 0xffff0000, v209
	v_pk_add_f32 v[2:3], v[2:3], v[248:249]
	v_pk_add_f32 v[4:5], v[4:5], v[250:251]
	v_cvt_pk_bf16_f32 v206, v6, v7
	v_cvt_pk_bf16_f32 v207, v8, v9
	v_cvt_pk_bf16_f32 v208, v2, v3
	v_cvt_pk_bf16_f32 v209, v4, v5
	v_add_u32_e32 v255, 0x165800, v245
	global_store_dwordx4 v255, v[206:209], s[98:99] offset:256
	v_fmac_f32_e32 v247, v6, v6
	v_fmac_f32_e32 v247, v7, v7
	v_fmac_f32_e32 v247, v8, v8
	v_fmac_f32_e32 v247, v9, v9
	v_fmac_f32_e32 v254, v2, v2
	v_fmac_f32_e32 v254, v3, v3
	v_fmac_f32_e32 v254, v4, v4
	v_fmac_f32_e32 v254, v5, v5
	v_add_f32_e32 v14, v247, v254
	ds_bpermute_b32 v127, v252, v126
	ds_bpermute_b32 v111, v252, v110
	ds_bpermute_b32 v95, v252, v94
	ds_bpermute_b32 v79, v252, v78
	ds_bpermute_b32 v63, v252, v62
	ds_bpermute_b32 v47, v252, v46
	ds_bpermute_b32 v31, v252, v30
	ds_bpermute_b32 v15, v252, v14
	s_waitcnt lgkmcnt(0)
	v_add_f32_e32 v126, v126, v127
	v_add_f32_e32 v110, v110, v111
	v_add_f32_e32 v94, v94, v95
	v_add_f32_e32 v78, v78, v79
	v_add_f32_e32 v62, v62, v63
	v_add_f32_e32 v46, v46, v47
	v_add_f32_e32 v30, v30, v31
	v_add_f32_e32 v14, v14, v15
	ds_bpermute_b32 v127, v253, v126
	ds_bpermute_b32 v111, v253, v110
	ds_bpermute_b32 v95, v253, v94
	ds_bpermute_b32 v79, v253, v78
	ds_bpermute_b32 v63, v253, v62
	ds_bpermute_b32 v47, v253, v46
	ds_bpermute_b32 v31, v253, v30
	ds_bpermute_b32 v15, v253, v14
	s_waitcnt lgkmcnt(0)
	v_add_f32_e32 v126, v126, v127
	v_add_f32_e32 v110, v110, v111
	v_add_f32_e32 v94, v94, v95
	v_add_f32_e32 v78, v78, v79
	v_add_f32_e32 v62, v62, v63
	v_add_f32_e32 v46, v46, v47
	v_add_f32_e32 v30, v30, v31
	v_add_f32_e32 v14, v14, v15
	v_cndmask_b32_e64 v248, 0, v126, s[2:3]
	v_cndmask_b32_e64 v249, 0, v110, s[2:3]
	v_cndmask_b32_e64 v248, v248, v94, s[4:5]
	v_cndmask_b32_e64 v249, v249, v78, s[4:5]
	v_cndmask_b32_e64 v248, v248, v62, s[6:7]
	v_cndmask_b32_e64 v249, v249, v46, s[6:7]
	v_cndmask_b32_e64 v248, v248, v30, s[8:9]
	v_cndmask_b32_e64 v249, v249, v14, s[8:9]
	v_lshl_add_u32 v250, s72, 8, v157
	v_add_u32_e32 v250, v158, v250
	v_lshlrev_b32_e32 v250, 2, v250
	global_atomic_add_f32 v250, v248, s[34:35]
	global_atomic_add_f32 v250, v249, s[34:35] offset:64

; #define GAS __attribute__((address_space(1)))
; __device__ __forceinline__ float row_rstd(const float* rowsq, int row) { return 1.0f / sqrtf(__hip_atomic_load(rowsq + row, __ATOMIC_RELAXED, __HIP_MEMORY_SCOPE_AGENT) * (1.0f / DM) + EPS); }
; #define GRID_BAR() xcd_barrier(bar)
; #define REPS(k) _Pragma("unroll") for (int rep_ = 0; rep_ <= ((DUP_MASK >> (k)) & 1); ++rep_)
; __global__ void __launch_bounds__(NWAVES * 64, 2) fwd_kernel(Args args) {
;     ...
;     if (IN(9)) {
;         if ((DUP_MASK >> 14) & 1) { _Pragma("nounroll") for (int r14_ = 0; r14_ < 8; ++r14_) GRID_BAR(); }
;     ...
;         REPS(9) { const bool dup_ = rep_ < ((DUP_MASK >> 9) & 1);
;         f32x4 gv[16];
; #pragma unroll
;         for (int j = 0; j < 16; ++j) gv[j] = *((const GAS f32x4*)g_final + lane + 64 * j);
;         for (int m = gw; m < MTOK; m += 2 * NGW) {
;             const int mb = (m + NGW < MTOK) ? m + NGW : m;
;             const float ra = bad ? __builtin_nanf("") : pg8::row_rstd(rsq3, m), rb = bad ? __builtin_nanf("") : pg8::row_rstd(rsq3, mb);
;             u32x2 ha[16], hb[16];
; #pragma unroll
;             for (int j = 0; j < 16; ++j) { ha[j] = *((const GAS u32x2*)(HB + (size_t)m * DM) + lane + 64 * j); hb[j] = *((const GAS u32x2*)(HB + (size_t)mb * DM) + lane + 64 * j); }
;             GAS f32x4* wa = (GAS f32x4*)((dup_ ? dummy_out : out) + (size_t)m * DM) + lane; GAS f32x4* wb = (GAS f32x4*)((dup_ ? dummy_out : out) + (size_t)mb * DM) + lane;
; #pragma unroll
.LBB0_1422:
	s_cmp_lt_i32 s96, 10
	s_cselect_b64 s[0:1], -1, 0
	s_cmp_gt_i32 s97, 9
	s_cselect_b64 s[2:3], -1, 0
	s_and_b64 s[0:1], s[0:1], s[2:3]
	s_andn2_b64 vcc, exec, s[0:1]
	v_readlane_b32 s0, v244, 2
	v_readlane_b32 s10, v244, 12
	v_readlane_b32 s11, v244, 13
	v_readlane_b32 s12, v244, 14
	v_readlane_b32 s13, v244, 15
	v_readlane_b32 s14, v244, 16
	v_readlane_b32 s15, v244, 17
	v_readlane_b32 s1, v244, 3
	v_readlane_b32 s2, v244, 4
	v_readlane_b32 s3, v244, 5
	v_readlane_b32 s4, v244, 6
	v_readlane_b32 s5, v244, 7
	v_readlane_b32 s6, v244, 8
	v_readlane_b32 s7, v244, 9
	v_readlane_b32 s8, v244, 10
	v_readlane_b32 s9, v244, 11
	s_cbranch_vccnz .LBB0_1432
	s_mov_b64 s[30:31], s[14:15]
	v_mov_b32_e32 v1, 0x4000
	global_load_dword v70, v1, s[30:31] offset:512 sc1
	s_mov_b64 s[28:29], s[12:13]
	s_cmpk_gt_i32 s18, 0x3fff
	s_cbranch_scc1 .LBB0_1432
	v_and_b32_e32 v68, 63, v0
	s_mov_b64 s[26:27], s[10:11]
	s_waitcnt vmcnt(34)
	v_lshlrev_b32_e32 v64, 4, v68
	v_mov_b32_e32 v65, 0
	v_lshl_add_u64 v[48:49], s[26:27], 0, v[64:65]
	v_add_co_u32_e32 v32, vcc, 0x1000, v48
	global_load_dwordx4 v[0:3], v64, s[10:11]
	global_load_dwordx4 v[4:7], v64, s[10:11] offset:1024
	global_load_dwordx4 v[8:11], v64, s[10:11] offset:2048
	global_load_dwordx4 v[12:15], v64, s[10:11] offset:3072
	v_addc_co_u32_e32 v33, vcc, 0, v49, vcc
	v_add_co_u32_e32 v50, vcc, 0x2000, v48
	global_load_dwordx4 v[16:19], v[32:33], off
	global_load_dwordx4 v[20:23], v[32:33], off offset:1024
	global_load_dwordx4 v[24:27], v[32:33], off offset:2048
	global_load_dwordx4 v[28:31], v[32:33], off offset:3072
	v_addc_co_u32_e32 v51, vcc, 0, v49, vcc
	v_add_co_u32_e32 v66, vcc, 0x3000, v48
	global_load_dwordx4 v[32:35], v[50:51], off
	global_load_dwordx4 v[36:39], v[50:51], off offset:1024
	global_load_dwordx4 v[40:43], v[50:51], off offset:2048
	global_load_dwordx4 v[44:47], v[50:51], off offset:3072
	v_addc_co_u32_e32 v67, vcc, 0, v49, vcc
	global_load_dwordx4 v[48:51], v[66:67], off
	global_load_dwordx4 v[52:55], v[66:67], off offset:1024
	global_load_dwordx4 v[56:59], v[66:67], off offset:2048
	global_load_dwordx4 v[60:63], v[66:67], off offset:3072
	s_ashr_i32 s19, s18, 31
	s_lshl_b32 s6, s22, 4
	s_lshl_b64 s[2:3], s[18:19], 14
	s_add_u32 s2, s28, s2
	s_addc_u32 s3, s29, s3
	s_waitcnt vmcnt(16)
	v_cmp_eq_u32_e64 s[0:1], 0, v70
	v_lshl_add_u64 v[70:71], s[2:3], 0, v[64:65]
	s_mov_b64 s[2:3], 0x3c00
	s_ashr_i32 s7, s6, 31
	v_lshl_add_u64 v[70:71], v[70:71], 0, s[2:3]
	s_lshl_b64 s[8:9], s[6:7], 14
	s_lshl_b64 s[2:3], s[18:19], 2
	s_add_u32 s17, s2, 0x60000
	v_lshlrev_b32_e32 v72, 3, v68
	v_mov_b32_e32 v73, v65
	s_addc_u32 s21, s3, 0
	s_mul_i32 s2, s18, 0x2080
	s_mov_b32 s3, 0
	v_lshl_add_u64 v[66:67], s[98:99], 0, v[72:73]
	v_lshl_add_u64 v[68:69], s[28:29], 0, v[64:65]
	s_movk_i32 s14, 0x1000
	s_movk_i32 s15, 0x2000
	s_movk_i32 s16, 0x3000
	s_lshl_b64 s[10:11], s[6:7], 2
	v_add_u32_e32 v72, s2, v72
	v_mov_b32_e32 v73, s3
	s_mul_i32 s12, s6, 0x2080
	s_mov_b32 s13, 0
	v_mov_b32_e32 v93, 0x358637bd
	s_mov_b32 s7, 0xf800000
	v_mov_b32_e32 v116, 0x260
	s_mov_b32 s19, 0x3a601000
	s_movk_i32 s22, 0xd000
	s_movk_i32 s23, 0xe000
	s_movk_i32 s24, 0xf000
	s_branch .LBB0_1426

; #define GAS __attribute__((address_space(1)))
; __device__ __forceinline__ float bf_lo(unsigned w) { return __uint_as_float(w << 16); }
; __device__ __forceinline__ float bf_hi(unsigned w) { return __uint_as_float(w & 0xffff0000u); }
; __device__ __forceinline__ float row_rstd(const float* rowsq, int row) { return 1.0f / sqrtf(__hip_atomic_load(rowsq + row, __ATOMIC_RELAXED, __HIP_MEMORY_SCOPE_AGENT) * (1.0f / DM) + EPS); }
; __global__ void __launch_bounds__(NWAVES * 64, 2) fwd_kernel(Args args) {
;     ...
;         for (int m = gw; m < MTOK; m += 2 * NGW) {
;             const int mb = (m + NGW < MTOK) ? m + NGW : m;
;             const float ra = bad ? __builtin_nanf("") : pg8::row_rstd(rsq3, m), rb = bad ? __builtin_nanf("") : pg8::row_rstd(rsq3, mb);
;             u32x2 ha[16], hb[16];
; #pragma unroll
;             for (int j = 0; j < 16; ++j) { ha[j] = *((const GAS u32x2*)(HB + (size_t)m * DM) + lane + 64 * j); hb[j] = *((const GAS u32x2*)(HB + (size_t)mb * DM) + lane + 64 * j); }
;             GAS f32x4* wa = (GAS f32x4*)((dup_ ? dummy_out : out) + (size_t)m * DM) + lane; GAS f32x4* wb = (GAS f32x4*)((dup_ ? dummy_out : out) + (size_t)mb * DM) + lane;
; #pragma unroll
;             for (int j = 0; j < 16; ++j) wa[64 * j] = (f32x4){bf_lo(ha[j].x), bf_hi(ha[j].x), bf_lo(ha[j].y), bf_hi(ha[j].y)} * ra * gv[j];
;             if (mb != m) {
; #pragma unroll
;                 for (int j = 0; j < 16; ++j) wb[64 * j] = (f32x4){bf_lo(hb[j].x), bf_hi(hb[j].x), bf_lo(hb[j].y), bf_hi(hb[j].y)} * rb * gv[j]; }
.LBB0_1430:
	s_waitcnt vmcnt(16)
	v_lshl_add_u64 v[74:75], s[30:31], 0, v[72:73]
	v_add_co_u32_e32 v76, vcc, 0x3a600000, v74
	s_mul_i32 s2, s4, 0x2080
	s_mov_b32 s3, 0
	s_nop 0
	v_addc_co_u32_e32 v77, vcc, 0, v75, vcc
	global_load_dwordx2 v[118:119], v[76:77], off
	global_load_dwordx2 v[120:121], v[76:77], off offset:512
	global_load_dwordx2 v[122:123], v[76:77], off offset:1024
	global_load_dwordx2 v[124:125], v[76:77], off offset:1536
	global_load_dwordx2 v[134:135], v[76:77], off offset:2048
	v_lshl_add_u64 v[78:79], v[66:67], 0, s[2:3]
	global_load_dwordx2 v[138:139], v[76:77], off offset:2560
	global_load_dwordx2 v[106:107], v[78:79], off
	global_load_dwordx2 v[104:105], v[78:79], off offset:512
	global_load_dwordx2 v[102:103], v[78:79], off offset:1024
	global_load_dwordx2 v[100:101], v[78:79], off offset:1536
	global_load_dwordx2 v[98:99], v[78:79], off offset:2048
	global_load_dwordx2 v[96:97], v[78:79], off offset:2560
	global_load_dwordx2 v[94:95], v[78:79], off offset:3072
	global_load_dwordx2 v[90:91], v[78:79], off offset:3584
	global_load_dwordx2 v[140:141], v[76:77], off offset:3072
	v_add_co_u32_e32 v136, vcc, s22, v70
	s_cmp_eq_u32 s18, s4
	s_nop 0
	v_addc_co_u32_e32 v137, vcc, -1, v71, vcc
	v_add_co_u32_e32 v74, vcc, s19, v74
	s_waitcnt vmcnt(13)
	v_lshlrev_b32_e32 v128, 16, v120
	v_addc_co_u32_e32 v75, vcc, 0, v75, vcc
	v_add_co_u32_e32 v126, vcc, s14, v78
	v_and_b32_e32 v129, 0xffff0000, v120
	s_nop 0
	v_addc_co_u32_e32 v127, vcc, 0, v79, vcc
	global_load_dwordx2 v[142:143], v[74:75], off
	global_load_dwordx2 v[144:145], v[74:75], off offset:512
	global_load_dwordx2 v[146:147], v[74:75], off offset:1024
	global_load_dwordx2 v[148:149], v[74:75], off offset:1536
	global_load_dwordx2 v[150:151], v[76:77], off offset:3584
	global_load_dwordx2 v[114:115], v[74:75], off offset:2048
	global_load_dwordx2 v[112:113], v[74:75], off offset:2560
	global_load_dwordx2 v[110:111], v[74:75], off offset:3072
	global_load_dwordx2 v[108:109], v[74:75], off offset:3584
	global_load_dwordx2 v[88:89], v[126:127], off
	global_load_dwordx2 v[86:87], v[126:127], off offset:512
	global_load_dwordx2 v[84:85], v[126:127], off offset:1024
	global_load_dwordx2 v[82:83], v[126:127], off offset:1536
	global_load_dwordx2 v[80:81], v[126:127], off offset:2048
	global_load_dwordx2 v[78:79], v[126:127], off offset:2560
	global_load_dwordx2 v[76:77], v[126:127], off offset:3072
	global_load_dwordx2 v[74:75], v[126:127], off offset:3584
	v_lshlrev_b32_e32 v126, 16, v118
	v_and_b32_e32 v127, 0xffff0000, v118
	v_lshlrev_b32_e32 v118, 16, v119
	v_and_b32_e32 v119, 0xffff0000, v119
	v_lshlrev_b32_e32 v120, 16, v121
	v_and_b32_e32 v121, 0xffff0000, v121
	s_waitcnt vmcnt(29)
	v_lshlrev_b32_e32 v130, 16, v122
	v_and_b32_e32 v131, 0xffff0000, v122
	v_lshlrev_b32_e32 v122, 16, v123
	v_and_b32_e32 v123, 0xffff0000, v123
	v_pk_mul_f32 v[126:127], v[92:93], v[126:127] op_sel_hi:[0,1]
	v_pk_mul_f32 v[118:119], v[92:93], v[118:119] op_sel_hi:[0,1]
	s_waitcnt vmcnt(28)
	v_lshlrev_b32_e32 v132, 16, v124
	v_and_b32_e32 v133, 0xffff0000, v124
	v_lshlrev_b32_e32 v124, 16, v125
	v_and_b32_e32 v125, 0xffff0000, v125
	v_pk_mul_f32 v[128:129], v[92:93], v[128:129] op_sel_hi:[0,1]
	v_pk_mul_f32 v[152:153], v[92:93], v[120:121] op_sel_hi:[0,1]
	v_pk_mul_f32 v[130:131], v[92:93], v[130:131] op_sel_hi:[0,1]
	v_pk_mul_f32 v[154:155], v[92:93], v[122:123] op_sel_hi:[0,1]
	v_pk_mul_f32 v[120:121], v[2:3], v[118:119]
	v_pk_mul_f32 v[118:119], v[0:1], v[126:127]
	v_pk_mul_f32 v[156:157], v[92:93], v[132:133] op_sel_hi:[0,1]
	v_pk_mul_f32 v[132:133], v[92:93], v[124:125] op_sel_hi:[0,1]
	v_pk_mul_f32 v[124:125], v[6:7], v[152:153]
	v_pk_mul_f32 v[122:123], v[4:5], v[128:129]
	v_pk_mul_f32 v[128:129], v[10:11], v[154:155]
	v_pk_mul_f32 v[126:127], v[8:9], v[130:131]
	global_store_dwordx4 v[136:137], v[118:121], off offset:-3072
	global_store_dwordx4 v[136:137], v[122:125], off offset:-2048
	global_store_dwordx4 v[136:137], v[126:129], off offset:-1024
	s_waitcnt vmcnt(30)
	v_lshlrev_b32_e32 v118, 16, v134
	v_and_b32_e32 v119, 0xffff0000, v134
	v_lshlrev_b32_e32 v120, 16, v135
	v_and_b32_e32 v121, 0xffff0000, v135
	v_add_co_u32_e32 v122, vcc, s23, v70
	v_pk_mul_f32 v[118:119], v[92:93], v[118:119] op_sel_hi:[0,1]
	v_pk_mul_f32 v[120:121], v[92:93], v[120:121] op_sel_hi:[0,1]
	v_addc_co_u32_e32 v123, vcc, -1, v71, vcc
	v_pk_mul_f32 v[120:121], v[18:19], v[120:121]
	v_pk_mul_f32 v[118:119], v[16:17], v[118:119]
	global_store_dwordx4 v[122:123], v[118:121], off offset:-3072
	v_pk_mul_f32 v[132:133], v[14:15], v[132:133]
	v_pk_mul_f32 v[130:131], v[12:13], v[156:157]
	s_waitcnt vmcnt(30)
	v_lshlrev_b32_e32 v118, 16, v138
	v_and_b32_e32 v119, 0xffff0000, v138
	v_lshlrev_b32_e32 v120, 16, v139
	v_and_b32_e32 v121, 0xffff0000, v139
	v_pk_mul_f32 v[118:119], v[92:93], v[118:119] op_sel_hi:[0,1]
	v_pk_mul_f32 v[120:121], v[92:93], v[120:121] op_sel_hi:[0,1]
	v_pk_mul_f32 v[120:121], v[22:23], v[120:121]
	v_pk_mul_f32 v[118:119], v[20:21], v[118:119]
	global_store_dwordx4 v[122:123], v[118:121], off offset:-2048
	global_store_dwordx4 v[122:123], v[130:133], off offset:-4096
	s_waitcnt vmcnt(23)
	v_lshlrev_b32_e32 v118, 16, v140
	v_and_b32_e32 v119, 0xffff0000, v140
	v_lshlrev_b32_e32 v120, 16, v141
	v_and_b32_e32 v121, 0xffff0000, v141
	v_pk_mul_f32 v[118:119], v[92:93], v[118:119] op_sel_hi:[0,1]
	v_pk_mul_f32 v[120:121], v[92:93], v[120:121] op_sel_hi:[0,1]
	v_pk_mul_f32 v[120:121], v[26:27], v[120:121]
	v_pk_mul_f32 v[118:119], v[24:25], v[118:119]
	global_store_dwordx4 v[122:123], v[118:121], off offset:-1024
	s_waitcnt vmcnt(19)
; #define GAS __attribute__((address_space(1)))
; __device__ __forceinline__ float bf_lo(unsigned w) { return __uint_as_float(w << 16); }
; __device__ __forceinline__ float bf_hi(unsigned w) { return __uint_as_float(w & 0xffff0000u); }
; __device__ __forceinline__ float row_rstd(const float* rowsq, int row) { return 1.0f / sqrtf(__hip_atomic_load(rowsq + row, __ATOMIC_RELAXED, __HIP_MEMORY_SCOPE_AGENT) * (1.0f / DM) + EPS); }
; __global__ void __launch_bounds__(NWAVES * 64, 2) fwd_kernel(Args args) {
;     ...
;         for (int m = gw; m < MTOK; m += 2 * NGW) {
;             const int mb = (m + NGW < MTOK) ? m + NGW : m;
;             const float ra = bad ? __builtin_nanf("") : pg8::row_rstd(rsq3, m), rb = bad ? __builtin_nanf("") : pg8::row_rstd(rsq3, mb);
;             u32x2 ha[16], hb[16];
; #pragma unroll
;             for (int j = 0; j < 16; ++j) { ha[j] = *((const GAS u32x2*)(HB + (size_t)m * DM) + lane + 64 * j); hb[j] = *((const GAS u32x2*)(HB + (size_t)mb * DM) + lane + 64 * j); }
;             GAS f32x4* wa = (GAS f32x4*)((dup_ ? dummy_out : out) + (size_t)m * DM) + lane; GAS f32x4* wb = (GAS f32x4*)((dup_ ? dummy_out : out) + (size_t)mb * DM) + lane;
; #pragma unroll
;             for (int j = 0; j < 16; ++j) wa[64 * j] = (f32x4){bf_lo(ha[j].x), bf_hi(ha[j].x), bf_lo(ha[j].y), bf_hi(ha[j].y)} * ra * gv[j];
;             if (mb != m) {
; #pragma unroll
;                 for (int j = 0; j < 16; ++j) wb[64 * j] = (f32x4){bf_lo(hb[j].x), bf_hi(hb[j].x), bf_lo(hb[j].y), bf_hi(hb[j].y)} * rb * gv[j]; }
	s_nop 0
	v_lshlrev_b32_e32 v118, 16, v150
	v_and_b32_e32 v119, 0xffff0000, v150
	v_lshlrev_b32_e32 v120, 16, v151
	v_and_b32_e32 v121, 0xffff0000, v151
	v_pk_mul_f32 v[118:119], v[92:93], v[118:119] op_sel_hi:[0,1]
	v_pk_mul_f32 v[120:121], v[92:93], v[120:121] op_sel_hi:[0,1]
	v_pk_mul_f32 v[120:121], v[30:31], v[120:121]
	v_pk_mul_f32 v[118:119], v[28:29], v[118:119]
	global_store_dwordx4 v[122:123], v[118:121], off
	v_add_co_u32_e32 v122, vcc, s24, v70
	s_nop 0
	v_lshlrev_b32_e32 v118, 16, v142
	v_and_b32_e32 v119, 0xffff0000, v142
	v_lshlrev_b32_e32 v120, 16, v143
	v_and_b32_e32 v121, 0xffff0000, v143
	v_pk_mul_f32 v[118:119], v[92:93], v[118:119] op_sel_hi:[0,1]
	v_pk_mul_f32 v[120:121], v[92:93], v[120:121] op_sel_hi:[0,1]
	v_pk_mul_f32 v[120:121], v[34:35], v[120:121]
	v_pk_mul_f32 v[118:119], v[32:33], v[118:119]
	v_addc_co_u32_e32 v123, vcc, -1, v71, vcc
	global_store_dwordx4 v[122:123], v[118:121], off offset:-3072
	s_nop 1
	v_lshlrev_b32_e32 v118, 16, v144
	v_and_b32_e32 v119, 0xffff0000, v144
	v_lshlrev_b32_e32 v120, 16, v145
	v_and_b32_e32 v121, 0xffff0000, v145
	v_pk_mul_f32 v[118:119], v[92:93], v[118:119] op_sel_hi:[0,1]
	v_pk_mul_f32 v[120:121], v[92:93], v[120:121] op_sel_hi:[0,1]
	v_pk_mul_f32 v[120:121], v[38:39], v[120:121]
	v_pk_mul_f32 v[118:119], v[36:37], v[118:119]
	global_store_dwordx4 v[122:123], v[118:121], off offset:-2048
	s_nop 1
	v_lshlrev_b32_e32 v118, 16, v146
	v_and_b32_e32 v119, 0xffff0000, v146
	v_lshlrev_b32_e32 v120, 16, v147
	v_and_b32_e32 v121, 0xffff0000, v147
	v_pk_mul_f32 v[118:119], v[92:93], v[118:119] op_sel_hi:[0,1]
	v_pk_mul_f32 v[120:121], v[92:93], v[120:121] op_sel_hi:[0,1]
	v_pk_mul_f32 v[120:121], v[42:43], v[120:121]
	v_pk_mul_f32 v[118:119], v[40:41], v[118:119]
	global_store_dwordx4 v[122:123], v[118:121], off offset:-1024
	s_nop 1
	v_lshlrev_b32_e32 v118, 16, v148
	v_and_b32_e32 v119, 0xffff0000, v148
	v_lshlrev_b32_e32 v120, 16, v149
	v_and_b32_e32 v121, 0xffff0000, v149
	v_pk_mul_f32 v[118:119], v[92:93], v[118:119] op_sel_hi:[0,1]
	v_pk_mul_f32 v[120:121], v[92:93], v[120:121] op_sel_hi:[0,1]
	v_pk_mul_f32 v[120:121], v[46:47], v[120:121]
	v_pk_mul_f32 v[118:119], v[44:45], v[118:119]
	global_store_dwordx4 v[70:71], v[118:121], off offset:-4096
	s_waitcnt vmcnt(23)
	s_nop 0
	v_lshlrev_b32_e32 v118, 16, v114
	v_and_b32_e32 v119, 0xffff0000, v114
	v_lshlrev_b32_e32 v114, 16, v115
	v_and_b32_e32 v115, 0xffff0000, v115
	v_pk_mul_f32 v[118:119], v[92:93], v[118:119] op_sel_hi:[0,1]
	v_pk_mul_f32 v[114:115], v[92:93], v[114:115] op_sel_hi:[0,1]
	v_pk_mul_f32 v[120:121], v[50:51], v[114:115]
	v_pk_mul_f32 v[118:119], v[48:49], v[118:119]
	s_waitcnt vmcnt(22)
	v_lshlrev_b32_e32 v114, 16, v112
	v_and_b32_e32 v115, 0xffff0000, v112
	v_lshlrev_b32_e32 v112, 16, v113
	v_and_b32_e32 v113, 0xffff0000, v113
	global_store_dwordx4 v[70:71], v[118:121], off offset:-3072
	v_pk_mul_f32 v[112:113], v[92:93], v[112:113] op_sel_hi:[0,1]
	s_nop 0
	v_pk_mul_f32 v[118:119], v[92:93], v[114:115] op_sel_hi:[0,1]
	v_pk_mul_f32 v[114:115], v[54:55], v[112:113]
	v_pk_mul_f32 v[112:113], v[52:53], v[118:119]
	global_store_dwordx4 v[70:71], v[112:115], off offset:-2048
	s_waitcnt vmcnt(23)
	s_nop 0
	v_lshlrev_b32_e32 v112, 16, v110
	v_and_b32_e32 v113, 0xffff0000, v110
	v_lshlrev_b32_e32 v110, 16, v111
	v_and_b32_e32 v111, 0xffff0000, v111
	v_pk_mul_f32 v[114:115], v[92:93], v[112:113] op_sel_hi:[0,1]
	v_pk_mul_f32 v[110:111], v[92:93], v[110:111] op_sel_hi:[0,1]
	v_pk_mul_f32 v[112:113], v[58:59], v[110:111]
	v_pk_mul_f32 v[110:111], v[56:57], v[114:115]
	global_store_dwordx4 v[70:71], v[110:113], off offset:-1024
	s_waitcnt vmcnt(23)
	s_nop 0
	v_lshlrev_b32_e32 v110, 16, v108
	v_and_b32_e32 v111, 0xffff0000, v108
	v_lshlrev_b32_e32 v108, 16, v109
	v_and_b32_e32 v109, 0xffff0000, v109
	v_pk_mul_f32 v[112:113], v[92:93], v[110:111] op_sel_hi:[0,1]
	v_pk_mul_f32 v[108:109], v[92:93], v[108:109] op_sel_hi:[0,1]
	v_pk_mul_f32 v[110:111], v[62:63], v[108:109]
	v_pk_mul_f32 v[108:109], v[60:61], v[112:113]
	global_store_dwordx4 v[70:71], v[108:111], off
	s_cbranch_scc1 .LBB0_1425
	s_nop 0
	v_lshlrev_b32_e32 v108, 16, v106
	v_and_b32_e32 v109, 0xffff0000, v106
	v_lshlrev_b32_e32 v106, 16, v107
	v_and_b32_e32 v107, 0xffff0000, v107
	s_lshl_b64 s[2:3], s[4:5], 14
	v_pk_mul_f32 v[112:113], v[64:65], v[108:109] op_sel_hi:[0,1]
	v_pk_mul_f32 v[106:107], v[64:65], v[106:107] op_sel_hi:[0,1]
	v_lshl_add_u64 v[110:111], v[68:69], 0, s[2:3]
	v_pk_mul_f32 v[108:109], v[2:3], v[106:107]
	v_pk_mul_f32 v[106:107], v[0:1], v[112:113]
	global_store_dwordx4 v[110:111], v[106:109], off
	s_nop 1
	v_lshlrev_b32_e32 v106, 16, v104
	v_and_b32_e32 v107, 0xffff0000, v104
	v_lshlrev_b32_e32 v104, 16, v105
	v_and_b32_e32 v105, 0xffff0000, v105
	v_pk_mul_f32 v[108:109], v[64:65], v[106:107] op_sel_hi:[0,1]
	v_pk_mul_f32 v[104:105], v[64:65], v[104:105] op_sel_hi:[0,1]
	v_pk_mul_f32 v[106:107], v[6:7], v[104:105]
	v_pk_mul_f32 v[104:105], v[4:5], v[108:109]
	global_store_dwordx4 v[110:111], v[104:107], off offset:1024
	s_nop 1
	v_lshlrev_b32_e32 v104, 16, v102
	v_and_b32_e32 v105, 0xffff0000, v102
	v_lshlrev_b32_e32 v102, 16, v103
	v_and_b32_e32 v103, 0xffff0000, v103
	v_pk_mul_f32 v[106:107], v[64:65], v[104:105] op_sel_hi:[0,1]
	v_pk_mul_f32 v[102:103], v[64:65], v[102:103] op_sel_hi:[0,1]
	v_pk_mul_f32 v[104:105], v[10:11], v[102:103]
	v_pk_mul_f32 v[102:103], v[8:9], v[106:107]
	global_store_dwordx4 v[110:111], v[102:105], off offset:2048
	s_nop 1
	v_lshlrev_b32_e32 v102, 16, v100
	v_and_b32_e32 v103, 0xffff0000, v100
	v_lshlrev_b32_e32 v100, 16, v101
	v_and_b32_e32 v101, 0xffff0000, v101
; #define GAS __attribute__((address_space(1)))
; __device__ __forceinline__ float bf_lo(unsigned w) { return __uint_as_float(w << 16); }
; __device__ __forceinline__ float bf_hi(unsigned w) { return __uint_as_float(w & 0xffff0000u); }
; __global__ void __launch_bounds__(NWAVES * 64, 2) fwd_kernel(Args args) {
;     ...
; #pragma unroll
;             for (int j = 0; j < 16; ++j) { ha[j] = *((const GAS u32x2*)(HB + (size_t)m * DM) + lane + 64 * j); hb[j] = *((const GAS u32x2*)(HB + (size_t)mb * DM) + lane + 64 * j); }
;             GAS f32x4* wa = (GAS f32x4*)((dup_ ? dummy_out : out) + (size_t)m * DM) + lane; GAS f32x4* wb = (GAS f32x4*)((dup_ ? dummy_out : out) + (size_t)mb * DM) + lane;
; #pragma unroll
;             for (int j = 0; j < 16; ++j) wa[64 * j] = (f32x4){bf_lo(ha[j].x), bf_hi(ha[j].x), bf_lo(ha[j].y), bf_hi(ha[j].y)} * ra * gv[j];
;             if (mb != m) {
; #pragma unroll
;                 for (int j = 0; j < 16; ++j) wb[64 * j] = (f32x4){bf_lo(hb[j].x), bf_hi(hb[j].x), bf_lo(hb[j].y), bf_hi(hb[j].y)} * rb * gv[j]; }
	v_pk_mul_f32 v[104:105], v[64:65], v[102:103] op_sel_hi:[0,1]
	v_pk_mul_f32 v[100:101], v[64:65], v[100:101] op_sel_hi:[0,1]
	v_pk_mul_f32 v[102:103], v[14:15], v[100:101]
	v_pk_mul_f32 v[100:101], v[12:13], v[104:105]
	global_store_dwordx4 v[110:111], v[100:103], off offset:3072
	s_nop 1
	v_lshlrev_b32_e32 v100, 16, v98
	v_and_b32_e32 v101, 0xffff0000, v98
	v_lshlrev_b32_e32 v98, 16, v99
	v_and_b32_e32 v99, 0xffff0000, v99
	v_pk_mul_f32 v[102:103], v[64:65], v[100:101] op_sel_hi:[0,1]
	v_pk_mul_f32 v[98:99], v[64:65], v[98:99] op_sel_hi:[0,1]
	v_pk_mul_f32 v[100:101], v[18:19], v[98:99]
	v_pk_mul_f32 v[98:99], v[16:17], v[102:103]
	v_add_co_u32_e32 v102, vcc, s14, v110
	s_nop 1
	v_addc_co_u32_e32 v103, vcc, 0, v111, vcc
	v_add_co_u32_e32 v104, vcc, s15, v110
	s_nop 1
	v_addc_co_u32_e32 v105, vcc, 0, v111, vcc
	global_store_dwordx4 v[104:105], v[98:101], off offset:-4096
	s_nop 1
	v_lshlrev_b32_e32 v98, 16, v96
	v_and_b32_e32 v99, 0xffff0000, v96
	v_lshlrev_b32_e32 v96, 16, v97
	v_and_b32_e32 v97, 0xffff0000, v97
	v_pk_mul_f32 v[100:101], v[64:65], v[98:99] op_sel_hi:[0,1]
	v_pk_mul_f32 v[96:97], v[64:65], v[96:97] op_sel_hi:[0,1]
	v_pk_mul_f32 v[98:99], v[22:23], v[96:97]
	v_pk_mul_f32 v[96:97], v[20:21], v[100:101]
	global_store_dwordx4 v[102:103], v[96:99], off offset:1024
	s_nop 1
	v_lshlrev_b32_e32 v96, 16, v94
	v_and_b32_e32 v97, 0xffff0000, v94
	v_lshlrev_b32_e32 v94, 16, v95
	v_and_b32_e32 v95, 0xffff0000, v95
	v_pk_mul_f32 v[98:99], v[64:65], v[96:97] op_sel_hi:[0,1]
	v_pk_mul_f32 v[94:95], v[64:65], v[94:95] op_sel_hi:[0,1]
	v_pk_mul_f32 v[96:97], v[26:27], v[94:95]
	v_pk_mul_f32 v[94:95], v[24:25], v[98:99]
	global_store_dwordx4 v[102:103], v[94:97], off offset:2048
	s_nop 1
	v_lshlrev_b32_e32 v94, 16, v90
	v_and_b32_e32 v95, 0xffff0000, v90
	v_lshlrev_b32_e32 v90, 16, v91
	v_and_b32_e32 v91, 0xffff0000, v91
	v_pk_mul_f32 v[94:95], v[64:65], v[94:95] op_sel_hi:[0,1]
	v_pk_mul_f32 v[90:91], v[64:65], v[90:91] op_sel_hi:[0,1]
	v_pk_mul_f32 v[96:97], v[30:31], v[90:91]
	v_pk_mul_f32 v[94:95], v[28:29], v[94:95]
	s_waitcnt vmcnt(30)
	v_lshlrev_b32_e32 v90, 16, v88
	v_and_b32_e32 v91, 0xffff0000, v88
	v_lshlrev_b32_e32 v88, 16, v89
	v_and_b32_e32 v89, 0xffff0000, v89
	global_store_dwordx4 v[102:103], v[94:97], off offset:3072
	v_pk_mul_f32 v[88:89], v[64:65], v[88:89] op_sel_hi:[0,1]
	s_nop 0
	v_pk_mul_f32 v[94:95], v[64:65], v[90:91] op_sel_hi:[0,1]
	v_pk_mul_f32 v[90:91], v[34:35], v[88:89]
	v_pk_mul_f32 v[88:89], v[32:33], v[94:95]
	global_store_dwordx4 v[104:105], v[88:91], off
	s_waitcnt vmcnt(31)
	s_nop 0
	v_lshlrev_b32_e32 v88, 16, v86
	v_and_b32_e32 v89, 0xffff0000, v86
	v_lshlrev_b32_e32 v86, 16, v87
	v_and_b32_e32 v87, 0xffff0000, v87
	v_pk_mul_f32 v[90:91], v[64:65], v[88:89] op_sel_hi:[0,1]
	v_pk_mul_f32 v[86:87], v[64:65], v[86:87] op_sel_hi:[0,1]
	v_pk_mul_f32 v[88:89], v[38:39], v[86:87]
	v_pk_mul_f32 v[86:87], v[36:37], v[90:91]
	global_store_dwordx4 v[104:105], v[86:89], off offset:1024
	s_waitcnt vmcnt(31)
	s_nop 0
	v_lshlrev_b32_e32 v86, 16, v84
	v_and_b32_e32 v87, 0xffff0000, v84
	v_lshlrev_b32_e32 v84, 16, v85
	v_and_b32_e32 v85, 0xffff0000, v85
	v_pk_mul_f32 v[88:89], v[64:65], v[86:87] op_sel_hi:[0,1]
	v_pk_mul_f32 v[84:85], v[64:65], v[84:85] op_sel_hi:[0,1]
	v_pk_mul_f32 v[86:87], v[42:43], v[84:85]
	v_pk_mul_f32 v[84:85], v[40:41], v[88:89]
	global_store_dwordx4 v[104:105], v[84:87], off offset:2048
	s_waitcnt vmcnt(31)
	s_nop 0
	v_lshlrev_b32_e32 v84, 16, v82
	v_and_b32_e32 v85, 0xffff0000, v82
	v_lshlrev_b32_e32 v82, 16, v83
	v_and_b32_e32 v83, 0xffff0000, v83
	v_pk_mul_f32 v[86:87], v[64:65], v[84:85] op_sel_hi:[0,1]
	v_pk_mul_f32 v[82:83], v[64:65], v[82:83] op_sel_hi:[0,1]
	v_pk_mul_f32 v[84:85], v[46:47], v[82:83]
	v_pk_mul_f32 v[82:83], v[44:45], v[86:87]
	global_store_dwordx4 v[104:105], v[82:85], off offset:3072
	s_waitcnt vmcnt(31)
	s_nop 0
	v_lshlrev_b32_e32 v82, 16, v80
	v_and_b32_e32 v83, 0xffff0000, v80
	v_lshlrev_b32_e32 v80, 16, v81
	v_and_b32_e32 v81, 0xffff0000, v81
	v_pk_mul_f32 v[84:85], v[64:65], v[82:83] op_sel_hi:[0,1]
	v_pk_mul_f32 v[80:81], v[64:65], v[80:81] op_sel_hi:[0,1]
	v_pk_mul_f32 v[82:83], v[50:51], v[80:81]
	v_pk_mul_f32 v[80:81], v[48:49], v[84:85]
	v_add_co_u32_e32 v84, vcc, s16, v110
	s_nop 1
	v_addc_co_u32_e32 v85, vcc, 0, v111, vcc
	global_store_dwordx4 v[84:85], v[80:83], off
	s_waitcnt vmcnt(31)
	s_nop 0
	v_lshlrev_b32_e32 v80, 16, v78
	v_and_b32_e32 v81, 0xffff0000, v78
	v_lshlrev_b32_e32 v78, 16, v79
	v_and_b32_e32 v79, 0xffff0000, v79
	v_pk_mul_f32 v[82:83], v[64:65], v[80:81] op_sel_hi:[0,1]
	v_pk_mul_f32 v[78:79], v[64:65], v[78:79] op_sel_hi:[0,1]
	v_pk_mul_f32 v[80:81], v[54:55], v[78:79]
	v_pk_mul_f32 v[78:79], v[52:53], v[82:83]
	global_store_dwordx4 v[84:85], v[78:81], off offset:1024
	s_waitcnt vmcnt(31)
	s_nop 0
	v_lshlrev_b32_e32 v78, 16, v76
	v_and_b32_e32 v79, 0xffff0000, v76
	v_lshlrev_b32_e32 v76, 16, v77
	v_and_b32_e32 v77, 0xffff0000, v77
	v_pk_mul_f32 v[80:81], v[64:65], v[78:79] op_sel_hi:[0,1]
	v_pk_mul_f32 v[76:77], v[64:65], v[76:77] op_sel_hi:[0,1]
	v_pk_mul_f32 v[78:79], v[58:59], v[76:77]
	v_pk_mul_f32 v[76:77], v[56:57], v[80:81]
	global_store_dwordx4 v[84:85], v[76:79], off offset:2048
	s_waitcnt vmcnt(31)
	s_nop 0
	v_lshlrev_b32_e32 v76, 16, v74
	v_and_b32_e32 v77, 0xffff0000, v74
	v_lshlrev_b32_e32 v74, 16, v75
	v_and_b32_e32 v75, 0xffff0000, v75
	v_pk_mul_f32 v[78:79], v[64:65], v[76:77] op_sel_hi:[0,1]
	v_pk_mul_f32 v[74:75], v[64:65], v[74:75] op_sel_hi:[0,1]
	v_pk_mul_f32 v[76:77], v[62:63], v[74:75]
	v_pk_mul_f32 v[74:75], v[60:61], v[78:79]
	global_store_dwordx4 v[84:85], v[74:77], off offset:3072
	s_branch .LBB0_1425

; __global__ void __launch_bounds__(NWAVES * 64, 2) fwd_kernel(Args args) {
	.amdhsa_kernel _Z10fwd_kernel4Args
		.amdhsa_group_segment_fixed_size 0
		.amdhsa_private_segment_fixed_size 0
		.amdhsa_kernarg_size 456
		.amdhsa_user_sgpr_count 2
		.amdhsa_user_sgpr_dispatch_ptr 0
		.amdhsa_user_sgpr_queue_ptr 0
		.amdhsa_user_sgpr_kernarg_segment_ptr 1
		.amdhsa_user_sgpr_dispatch_id 0
		.amdhsa_user_sgpr_kernarg_preload_length 0
		.amdhsa_user_sgpr_kernarg_preload_offset 0
		.amdhsa_user_sgpr_private_segment_size 0
		.amdhsa_uses_dynamic_stack 0
		.amdhsa_enable_private_segment 0
		.amdhsa_system_sgpr_workgroup_id_x 1
		.amdhsa_system_sgpr_workgroup_id_y 0
		.amdhsa_system_sgpr_workgroup_id_z 0
		.amdhsa_system_sgpr_workgroup_info 0
		.amdhsa_system_vgpr_workitem_id 0
		.amdhsa_next_free_vgpr 256
		.amdhsa_next_free_sgpr 100
		.amdhsa_accum_offset 256
		.amdhsa_reserve_vcc 1
		.amdhsa_float_round_mode_32 0
		.amdhsa_float_round_mode_16_64 0
		.amdhsa_float_denorm_mode_32 3
		.amdhsa_float_denorm_mode_16_64 3
		.amdhsa_dx10_clamp 1
		.amdhsa_ieee_mode 1
		.amdhsa_fp16_overflow 0
		.amdhsa_tg_split 0
		.amdhsa_exception_fp_ieee_invalid_op 0
		.amdhsa_exception_fp_denorm_src 0
		.amdhsa_exception_fp_ieee_div_zero 0
		.amdhsa_exception_fp_ieee_overflow 0
		.amdhsa_exception_fp_ieee_underflow 0
		.amdhsa_exception_fp_ieee_inexact 0
		.amdhsa_exception_int_div_zero 0
	.end_amdhsa_kernel

; __global__ void __launch_bounds__(NWAVES * 64, 2) fwd_kernel(Args args) {
amdhsa.kernels:
  - .agpr_count:     0
    .args:
      - .offset:         0
        .size:           200
        .value_kind:     by_value
      - .offset:         200
        .size:           4
        .value_kind:     hidden_block_count_x
      - .offset:         204
        .size:           4
        .value_kind:     hidden_block_count_y
      - .offset:         208
        .size:           4
        .value_kind:     hidden_block_count_z
      - .offset:         212
        .size:           2
        .value_kind:     hidden_group_size_x
      - .offset:         214
        .size:           2
        .value_kind:     hidden_group_size_y
      - .offset:         216
        .size:           2
        .value_kind:     hidden_group_size_z
      - .offset:         218
        .size:           2
        .value_kind:     hidden_remainder_x
      - .offset:         220
        .size:           2
        .value_kind:     hidden_remainder_y
      - .offset:         222
        .size:           2
        .value_kind:     hidden_remainder_z
      - .offset:         240
        .size:           8
        .value_kind:     hidden_global_offset_x
      - .offset:         248
        .size:           8
        .value_kind:     hidden_global_offset_y
      - .offset:         256
        .size:           8
        .value_kind:     hidden_global_offset_z
      - .offset:         264
        .size:           2
        .value_kind:     hidden_grid_dims
      - .offset:         320
        .size:           4
        .value_kind:     hidden_dynamic_lds_size
    .group_segment_fixed_size: 0
    .kernarg_segment_align: 8
    .kernarg_segment_size: 456
    .language:       OpenCL C
    .language_version:
      - 2
      - 0
    .max_flat_workgroup_size: 512
    .name:           _Z10fwd_kernel4Args
    .private_segment_fixed_size: 0
    .sgpr_count:     106
    .sgpr_spill_count: 63
    .symbol:         _Z10fwd_kernel4Args.kd
    .uniform_work_group_size: 1
    .uses_dynamic_stack: false
    .vgpr_count:     256
    .vgpr_spill_count: 0
    .wavefront_size: 64
